# x15 + dilated attention: K-DMA address calc and K DMA issue interleaved into the QK MFMA chain (first QK MFMA starts right after the K fragment reads)
# speedup vs baseline: 1.0402x; 1.0056x over previous
.LBB0_87:
	s_waitcnt lgkmcnt(0)
	v_mfma_f32_32x32x16_bf16 v[66:81], v[66:69], v[82:85], 0
	ds_write_b128 v243, v[114:117]
	ds_write_b128 v244, v[118:121] offset:256
	ds_write_b128 v245, v[122:125] offset:2048
	ds_write_b128 v246, v[126:129] offset:2304
	ds_write_b128 v243, v[130:133] offset:4096
	ds_write_b128 v244, v[134:137] offset:4352
	ds_write_b128 v245, v[138:141] offset:6144
	ds_write_b128 v246, v[142:145] offset:6400
	v_mfma_f32_32x32x16_bf16 v[66:81], v[170:173], v[86:89], v[66:81]
	v_mov_b32_e32 v64, s43
	v_mad_u32_u24 v118, s44, v219, v64
	v_med3_i32 v64, v118, 0, v232
	v_mul_u32_u24_e32 v64, 0x3000, v64
	v_lshl_add_u64 v[114:115], s[22:23], 0, v[64:65]
	s_lshl_b32 s10, s44, 3
	v_lshl_add_u64 v[116:117], v[114:115], 0, v[188:189]
	v_add_u32_e32 v118, s10, v118
	s_mov_b32 m0, s16
	v_lshl_add_u64 v[116:117], v[116:117], 0, s[92:93]
	v_lshl_add_u64 v[114:115], v[114:115], 0, v[190:191]
	v_med3_i32 v64, v118, 0, v232
	global_load_lds_dwordx4 v[116:117], off
	v_lshl_add_u64 v[114:115], v[114:115], 0, s[92:93]
	s_mov_b32 m0, s30
	v_mul_u32_u24_e32 v64, 0x3000, v64
	global_load_lds_dwordx4 v[114:115], off
	v_mfma_f32_32x32x16_bf16 v[66:81], v[158:161], v[90:93], v[66:81]
	v_lshl_add_u64 v[114:115], s[22:23], 0, v[64:65]
	v_lshl_add_u64 v[116:117], v[192:193], 1, v[114:115]
	v_add_u32_e32 v118, s10, v118
	v_lshl_add_u64 v[116:117], v[116:117], 0, s[92:93]
	s_mov_b32 m0, s31
	v_lshl_add_u64 v[114:115], v[196:197], 1, v[114:115]
	v_med3_i32 v64, v118, 0, v232
	global_load_lds_dwordx4 v[116:117], off
	v_lshl_add_u64 v[114:115], v[114:115], 0, s[92:93]
	s_mov_b32 m0, s34
	v_mul_u32_u24_e32 v64, 0x3000, v64
	global_load_lds_dwordx4 v[114:115], off
	v_lshl_add_u64 v[114:115], s[22:23], 0, v[64:65]
	v_lshl_add_u64 v[116:117], v[114:115], 0, v[188:189]
	v_add_u32_e32 v64, s10, v118
	v_lshl_add_u64 v[116:117], v[116:117], 0, s[92:93]
	s_mov_b32 m0, s35
	v_mfma_f32_32x32x16_bf16 v[66:81], v[162:165], v[94:97], v[66:81]
	v_lshl_add_u64 v[114:115], v[114:115], 0, v[190:191]
	v_med3_i32 v64, v64, 0, v232
	global_load_lds_dwordx4 v[116:117], off
	v_lshl_add_u64 v[114:115], v[114:115], 0, s[92:93]
	s_mov_b32 m0, s2
	v_mul_u32_u24_e32 v64, 0x3000, v64
	global_load_lds_dwordx4 v[114:115], off
	v_lshl_add_u64 v[114:115], s[22:23], 0, v[64:65]
	v_lshl_add_u64 v[116:117], v[198:199], 1, v[114:115]
	v_lshl_add_u64 v[116:117], v[116:117], 0, s[92:93]
	s_mov_b32 m0, s36
	v_lshl_add_u64 v[114:115], v[200:201], 1, v[114:115]
	global_load_lds_dwordx4 v[116:117], off
	v_lshl_add_u64 v[114:115], v[114:115], 0, s[92:93]
	s_mov_b32 m0, s14
	global_load_lds_dwordx4 v[114:115], off
	s_mov_b64 s[10:11], 0
	v_mfma_f32_32x32x16_bf16 v[66:81], v[154:157], v[98:101], v[66:81]
	v_mul_lo_u32 v64, s44, v221
	v_add_u32_e32 v116, s43, v64
	v_med3_i32 v64, v116, 0, v232
	s_lshl_b32 s20, s44, 2
	v_mul_u32_u24_e32 v64, 0x3000, v64
	v_add_u32_e32 v122, s20, v116
	v_lshl_add_u64 v[114:115], v[202:203], 0, v[64:65]
	v_med3_i32 v64, v122, 0, v232
	v_mul_u32_u24_e32 v64, 0x3000, v64
	v_add_u32_e32 v124, s20, v122
	v_lshl_add_u64 v[118:119], v[202:203], 0, v[64:65]
	v_med3_i32 v64, v124, 0, v232
	v_mfma_f32_32x32x16_bf16 v[66:81], v[166:169], v[102:105], v[66:81]
	v_mul_u32_u24_e32 v64, 0x3000, v64
	v_add_u32_e32 v130, s20, v124
	v_lshl_add_u64 v[122:123], v[202:203], 0, v[64:65]
	v_med3_i32 v64, v130, 0, v232
	v_mul_u32_u24_e32 v64, 0x3000, v64
	v_add_u32_e32 v132, s20, v130
	v_lshl_add_u64 v[126:127], v[202:203], 0, v[64:65]
	v_med3_i32 v64, v132, 0, v232
	v_mul_u32_u24_e32 v64, 0x3000, v64
	v_add_u32_e32 v138, s20, v132
	v_lshl_add_u64 v[130:131], v[202:203], 0, v[64:65]
	v_med3_i32 v64, v138, 0, v232
	v_mfma_f32_32x32x16_bf16 v[66:81], v[150:153], v[106:109], v[66:81]
	v_mul_u32_u24_e32 v64, 0x3000, v64
	v_add_u32_e32 v140, s20, v138
	v_lshl_add_u64 v[134:135], v[202:203], 0, v[64:65]
	v_med3_i32 v64, v140, 0, v232
	v_mul_u32_u24_e32 v64, 0x3000, v64
	v_lshl_add_u64 v[138:139], v[202:203], 0, v[64:65]
	v_add_u32_e32 v64, s20, v140
	v_med3_i32 v64, v64, 0, v232
	v_mul_u32_u24_e32 v64, 0x3000, v64
	v_lshl_add_u64 v[142:143], v[202:203], 0, v[64:65]
	v_mfma_f32_32x32x16_bf16 v[66:81], v[146:149], v[110:113], v[66:81]
	global_load_dwordx4 v[114:117], v[114:115], off
	s_nop 0
	global_load_dwordx4 v[118:121], v[118:119], off
	s_nop 0
	global_load_dwordx4 v[122:125], v[122:123], off
	s_nop 0
	global_load_dwordx4 v[126:129], v[126:127], off
	s_nop 0
	global_load_dwordx4 v[130:133], v[130:131], off
	s_nop 0
	global_load_dwordx4 v[134:137], v[134:135], off
	s_nop 0
	global_load_dwordx4 v[138:141], v[138:139], off
	s_nop 0
	global_load_dwordx4 v[142:145], v[142:143], off
	s_branch .LBB0_90
.LBB0_88:
	s_waitcnt lgkmcnt(0)
	v_mfma_f32_32x32x16_bf16 v[66:81], v[66:69], v[82:85], 0
	s_xor_b64 s[10:11], s[20:21], -1
	ds_write_b128 v243, v[114:117]
	ds_write_b128 v244, v[118:121] offset:256
	ds_write_b128 v245, v[122:125] offset:2048
	ds_write_b128 v246, v[126:129] offset:2304
	ds_write_b128 v243, v[130:133] offset:4096
	ds_write_b128 v244, v[134:137] offset:4352
	ds_write_b128 v245, v[138:141] offset:6144
	ds_write_b128 v246, v[142:145] offset:6400
	v_mfma_f32_32x32x16_bf16 v[66:81], v[170:173], v[86:89], v[66:81]
	v_mfma_f32_32x32x16_bf16 v[66:81], v[158:161], v[90:93], v[66:81]
	v_mfma_f32_32x32x16_bf16 v[66:81], v[162:165], v[94:97], v[66:81]
	v_mfma_f32_32x32x16_bf16 v[66:81], v[154:157], v[98:101], v[66:81]
	v_mfma_f32_32x32x16_bf16 v[66:81], v[166:169], v[102:105], v[66:81]
	v_mfma_f32_32x32x16_bf16 v[66:81], v[150:153], v[106:109], v[66:81]
	v_mfma_f32_32x32x16_bf16 v[66:81], v[146:149], v[110:113], v[66:81]
	s_nop 3
